# ping-pong attention: waves 4-7 issue their LDS-DMA pieces in their load segment (compute segments of both halves are now DMA-free)
# speedup vs baseline: 1.0207x; 1.0033x over previous
; DI void attn_unit(const Params& p, LAS unsigned char* ldsu, int kind, int b, int h, int u, float lam) {
;     ...
;     f32x16 O[4]; float l = 0.f;
; #pragma unroll
;     for (int v = 0; v < 4; ++v)
; #pragma unroll
;         for (int i = 0; i < 16; ++i) O[v][i] = 0.f;
;     const int i16 = lane & 15, q4 = i16 >> 2, p4 = i16 & 3, blk = (lane >> 4) & 1;
;     const int kboff = qr * KRS + 16 * hh + cmp * 128, vboff = SLOT_V + (4 * hh + q4) * VRS + blk * 32 + p4 * 8;
;     ...
;     if (kind == 0) {
;         unsigned poff[5]; dma_offsets(poff, wid, lane);
;         auto stage = [&](int t) { if (t >= ntl) t = ntl - 1; const int row0 = t == 0 ? ROW_M : b * SEQ + (t - 1) * 64;
;             dma_tile(lds + (t & 3) * SLOT_B, KB + (size_t)row0 * 512 + hc, VB + (size_t)row0 * 512 + hc, poff, wid); };
;         stage(0); stage(1); stage(2);
;         asm volatile("s_waitcnt vmcnt(10)" ::: "memory");
;         __syncthreads();
.LBB0_743:
	s_add_i32 s6, s31, -1
	v_readlane_b32 s7, v254, 22
	s_add_u32 s22, s7, s62
	v_readlane_b32 s7, v254, 23
	s_addc_u32 s23, s7, 0
	v_readlane_b32 s7, v254, 24
	s_add_u32 s24, s7, s62
	v_readlane_b32 s7, v254, 25
	s_addc_u32 s25, s7, 0
	s_and_b64 s[10:11], s[0:1], exec
	v_lshlrev_b32_e32 v0, 10, v0
	v_min_i32_e32 v2, 15, v2
	s_cselect_b32 s21, s23, s25
	s_cselect_b32 s20, s22, s24
	s_lshl_b32 s7, s12, 10
	v_lshl_or_b32 v132, v2, 4, v0
	s_add_i32 s26, s7, 0
	s_mov_b32 s10, m0
	s_mov_b32 m0, s26
	s_nop 0
	global_load_lds_dwordx4 v132, s[20:21]
	s_mov_b32 m0, s10
	s_lshl_b32 s10, s13, 10
	s_add_i32 s27, s10, 0
	s_add_i32 s11, s27, 0x400
	v_lshlrev_b32_e32 v3, 10, v3
	v_min_i32_e32 v4, 15, v4
	s_and_b64 s[12:13], exec, s[8:9]
	v_lshl_or_b32 v131, v4, 4, v3
	s_mov_b32 s12, m0
	s_mov_b32 m0, s11
	s_nop 0
	global_load_lds_dwordx4 v131, s[20:21]
	s_mov_b32 m0, s12
	s_cselect_b32 s21, s23, s25
	s_cselect_b32 s20, s22, s24
	s_lshl_b32 s11, s18, 10
	s_add_i32 s22, s11, 0
	v_lshlrev_b32_e32 v5, 10, v5
	v_min_i32_e32 v6, 15, v6
	s_add_i32 s12, s22, 0x800
	v_lshl_or_b32 v130, v6, 4, v5
	s_mov_b32 s13, m0
	s_mov_b32 m0, s12
	s_nop 0
	global_load_lds_dwordx4 v130, s[20:21]
	s_mov_b32 m0, s13
	s_lshl_b32 s12, s19, 10
	s_add_i32 s23, s12, 0
	v_lshlrev_b32_e32 v7, 10, v7
	v_min_i32_e32 v8, 15, v8
	s_add_i32 s13, s23, 0xc00
	v_lshl_or_b32 v129, v8, 4, v7
	s_mov_b32 s18, m0
	s_mov_b32 m0, s13
	s_nop 0
	global_load_lds_dwordx4 v129, s[20:21]
	s_mov_b32 m0, s18
	s_lshl_b32 s13, s17, 10
	s_add_i32 s24, s13, 0
	v_lshlrev_b32_e32 v0, 10, v9
	v_min_i32_e32 v2, 15, v10
	s_add_i32 s17, s24, 0x1000
	v_lshl_or_b32 v133, v2, 4, v0
	s_mov_b32 s18, m0
	s_mov_b32 m0, s17
	s_nop 0
	global_load_lds_dwordx4 v133, s[20:21]
	s_mov_b32 m0, s18
	s_lshl_b32 s17, s16, 12
	s_sub_i32 s17, s17, 64
	s_lshl_b32 s16, s16, 22
	v_readlane_b32 s36, v254, 14
	s_add_u32 s18, s36, s16
	v_readlane_b32 s37, v254, 15
	s_addc_u32 s19, s37, 0
	s_add_u32 s20, s18, s62
	s_addc_u32 s21, s19, 0
	v_readlane_b32 s38, v254, 16
	s_add_u32 s18, s38, s16
	v_readlane_b32 s39, v254, 17
	s_addc_u32 s19, s39, 0
	s_add_u32 s25, s18, s62
	s_addc_u32 s34, s19, 0
	s_and_b64 s[18:19], s[0:1], exec
	s_cselect_b32 s19, s21, s34
	s_cselect_b32 s18, s20, s25
	s_add_i32 s26, s26, 0x9400
	s_mov_b32 s35, m0
	s_mov_b32 m0, s26
	s_nop 0
	global_load_lds_dwordx4 v132, s[18:19]
	s_mov_b32 m0, s35
	s_add_i32 s27, s27, 0x9800
	s_mov_b32 s26, m0
	s_mov_b32 m0, s27
	s_nop 0
	global_load_lds_dwordx4 v131, s[18:19]
	s_mov_b32 m0, s26
	s_and_b64 s[18:19], exec, s[8:9]
	s_cselect_b32 s19, s21, s34
	s_cselect_b32 s18, s20, s25
	s_add_i32 s22, s22, 0x9c00
	s_mov_b32 s20, m0
	s_mov_b32 m0, s22
	s_nop 0
	global_load_lds_dwordx4 v130, s[18:19]
	s_mov_b32 m0, s20
	s_add_i32 s23, s23, 0xa000
	s_mov_b32 s20, m0
	s_mov_b32 m0, s23
	s_nop 0
	global_load_lds_dwordx4 v129, s[18:19]
	s_mov_b32 m0, s20
	s_add_i32 s24, s24, 0xa400
	s_bitset1_b32 s16, 16
	s_mov_b32 s20, m0
	s_mov_b32 m0, s24
	s_nop 0
	global_load_lds_dwordx4 v133, s[18:19]
	s_mov_b32 m0, s20
	s_add_u32 s18, s36, s16
	s_addc_u32 s19, s37, 0
	s_add_u32 s20, s18, s62
	s_addc_u32 s21, s19, 0
	s_add_u32 s16, s38, s16
	s_addc_u32 s18, s39, 0
	s_add_u32 s16, s16, s62
	s_addc_u32 s22, s18, 0
	s_and_b64 s[18:19], s[0:1], exec
	v_readlane_b32 s25, v254, 30
	s_cselect_b32 s19, s21, s22
	s_cselect_b32 s18, s20, s16
	s_add_i32 s23, s25, s7
	s_mov_b32 s24, m0
	s_mov_b32 m0, s23
	s_nop 0
	global_load_lds_dwordx4 v132, s[18:19]
	s_mov_b32 m0, s24
	s_add_i32 s23, s25, s10
	s_addk_i32 s23, 0x400
	s_mov_b32 s24, m0
	s_mov_b32 m0, s23
	s_nop 0
	global_load_lds_dwordx4 v131, s[18:19]
	s_mov_b32 m0, s24
	s_and_b64 s[18:19], exec, s[8:9]
	s_cselect_b32 s19, s21, s22
	s_cselect_b32 s18, s20, s16
	s_add_i32 s16, s25, s11
	s_addk_i32 s16, 0x800
	s_mov_b32 s20, m0
	s_mov_b32 m0, s16
	s_nop 0
	global_load_lds_dwordx4 v130, s[18:19]
	s_mov_b32 m0, s20
	s_add_i32 s16, s25, s12
	s_addk_i32 s16, 0xc00
	s_mov_b32 s20, m0
	s_mov_b32 m0, s16
	s_nop 0
	global_load_lds_dwordx4 v129, s[18:19]
	s_mov_b32 m0, s20
	s_add_i32 s16, s25, s13
	s_addk_i32 s16, 0x1000
	s_mov_b32 s20, m0
	s_mov_b32 m0, s16
	s_nop 0
	global_load_lds_dwordx4 v133, s[18:19]
	s_mov_b32 m0, s20
	s_add_u32 s16, s36, s62
	s_waitcnt vmcnt(10)
	s_addc_u32 s18, s37, 0
	v_mov_b32_e32 v14, v1
	v_mov_b32_e32 v15, v1
	s_add_u32 s19, s38, s62
	v_mov_b32_e32 v0, v1
	v_mov_b32_e32 v2, v1
	v_mov_b32_e32 v3, v1
	v_mov_b32_e32 v4, v1
	v_mov_b32_e32 v5, v1
	v_mov_b32_e32 v6, v1
	v_mov_b32_e32 v7, v1
	v_mov_b32_e32 v8, v1
	v_mov_b32_e32 v9, v1
	v_mov_b32_e32 v10, v1
	v_mov_b32_e32 v11, v1
	v_mov_b32_e32 v12, v1
	v_mov_b32_e32 v13, v1
	v_mov_b64_e32 v[30:31], v[14:15]
	v_mov_b64_e32 v[46:47], v[14:15]
	v_mov_b64_e32 v[62:63], v[14:15]
	v_mov_b64_e32 v[78:79], v[14:15]
	s_addc_u32 s20, s39, 0
	v_add3_u32 v134, v176, v177, v178
	s_mov_b32 s21, 0
	v_mov_b32_e32 v175, 0
	v_mov_b64_e32 v[28:29], v[12:13]
	v_mov_b64_e32 v[26:27], v[10:11]
	v_mov_b64_e32 v[24:25], v[8:9]
	v_mov_b64_e32 v[22:23], v[6:7]
	v_mov_b64_e32 v[20:21], v[4:5]
	v_mov_b64_e32 v[18:19], v[2:3]
	v_mov_b64_e32 v[16:17], v[0:1]
	v_mov_b64_e32 v[44:45], v[12:13]
	v_mov_b64_e32 v[42:43], v[10:11]
	v_mov_b64_e32 v[40:41], v[8:9]
	v_mov_b64_e32 v[38:39], v[6:7]
	v_mov_b64_e32 v[36:37], v[4:5]
	v_mov_b64_e32 v[34:35], v[2:3]
	v_mov_b64_e32 v[32:33], v[0:1]
	v_mov_b64_e32 v[60:61], v[12:13]
	v_mov_b64_e32 v[58:59], v[10:11]
	v_mov_b64_e32 v[56:57], v[8:9]
	v_mov_b64_e32 v[54:55], v[6:7]
	v_mov_b64_e32 v[52:53], v[4:5]
	v_mov_b64_e32 v[50:51], v[2:3]
	v_mov_b64_e32 v[48:49], v[0:1]
	v_mov_b64_e32 v[76:77], v[12:13]
	v_mov_b64_e32 v[74:75], v[10:11]
	v_mov_b64_e32 v[72:73], v[8:9]
	v_mov_b64_e32 v[70:71], v[6:7]
	v_mov_b64_e32 v[68:69], v[4:5]
	v_mov_b64_e32 v[66:67], v[2:3]
	v_mov_b64_e32 v[64:65], v[0:1]
	s_waitcnt lgkmcnt(0)
	s_barrier
	s_and_b64 vcc, exec, s[0:1]
	s_cbranch_vccnz .LBB0_745
	s_barrier
	s_branch .LBB0_745

; #define LAS __attribute__((address_space(3)))
; DI s16x4 vtr(const LAS char* p) { return __builtin_bit_cast(s16x4, __builtin_amdgcn_ds_read_tr16_b64_v4i16((LAS v4i16_t*)p)); }
; DI bf16x8 cat4(s16x4 lo, s16x4 hi) { return __builtin_shufflevector(lo, hi, 0, 1, 2, 3, 4, 5, 6, 7); }
; #define MFMA32(a, b, c) __builtin_amdgcn_mfma_f32_32x32x16_bf16((a), (b), (c), 0, 0, 0)
; DI void attn_qk(const LAS char* kb, const bf16x8 (&qf)[4], bf16x8 (&pf)[4], float& l) {
;     ...
;     bf16x8 k0[4], k1[4];
; #pragma unroll
;     for (int s = 0; s < 4; ++s) k0[s] = *(const LAS bf16x8*)(kb + 32 * s);
; #pragma unroll
;     for (int s = 0; s < 4; ++s) k1[s] = *(const LAS bf16x8*)(kb + 32 * KRS + 32 * s);
; DI void attn_pv(const LAS char* vb, const bf16x8 (&pf)[4], f32x16 (&O)[4]) {
;     s16x4 va[8], vc[8];
; #pragma unroll
;     for (int ks = 0; ks < 4; ++ks) { va[2 * ks] = vtr(vb + ks * 16 * VRS); va[2 * ks + 1] = vtr(vb + (ks * 16 + 8) * VRS); }
; #pragma unroll
;     for (int ks = 0; ks < 4; ++ks) { vc[2 * ks] = vtr(vb + ks * 16 * VRS + 64); vc[2 * ks + 1] = vtr(vb + (ks * 16 + 8) * VRS + 64); }
; #pragma unroll
;     for (int ks = 0; ks < 4; ++ks) O[0] = MFMA32(cat4(va[2 * ks], va[2 * ks + 1]), pf[ks], O[0]);
; #pragma unroll
;     for (int ks = 0; ks < 4; ++ks) { va[2 * ks] = vtr(vb + ks * 16 * VRS + 128); va[2 * ks + 1] = vtr(vb + (ks * 16 + 8) * VRS + 128); }
; DI void attn_unit(const Params& p, LAS unsigned char* ldsu, int kind, int b, int h, int u, float lam) {
;     ...
;             stage(t + 3);
;             const LAS char* sp = lds + (t & 3) * SLOT_B;
;             if (t <= my_last) { bf16x8 pf[4]; attn_qk(sp + kboff, qf, pf, l); attn_pv(sp + vboff, pf, O); }
.LattnB:
	s_add_i32 s22, s21, 3
	s_min_i32 s24, s22, s6
	s_lshl_b32 s22, s24, 6
	s_add_i32 s22, s17, s22
	s_and_b32 s24, s24, 3
	s_ashr_i32 s23, s22, 31
	s_mul_i32 s24, s24, 0x9400
	s_lshl_b64 s[22:23], s[22:23], 10
	s_add_u32 s25, s16, s22
	s_addc_u32 s26, s18, s23
	s_add_u32 s27, s19, s22
	s_addc_u32 s34, s20, s23
	s_cmp_gt_i32 s21, s29
	s_cbranch_scc1 .LattnB_skip
	s_and_b32 s35, s21, 3
	s_mul_i32 s35, s35, 0x9400
	v_add_u32_e32 v0, s35, v174
	v_add_u32_e32 v14, s35, v134
	ds_read_b128 v[2:5], v0
	ds_read_b128 v[6:9], v0 offset:32
	ds_read_b128 v[10:13], v0 offset:64
	ds_read_b128 v[136:139], v0 offset:96
	ds_read_b128 v[140:143], v0 offset:8704
	ds_read_b128 v[144:147], v0 offset:8736
	ds_read_b128 v[148:151], v0 offset:8768
	ds_read_b128 v[196:199], v0 offset:8800
	ds_read_b64_tr_b16 v[200:201], v14 offset:17408
	ds_read_b64_tr_b16 v[202:203], v14 offset:19968
	ds_read_b64_tr_b16 v[204:205], v14 offset:17472
	ds_read_b64_tr_b16 v[206:207], v14 offset:20032
	ds_read_b64_tr_b16 v[208:209], v14 offset:17536
	ds_read_b64_tr_b16 v[210:211], v14 offset:20096
	ds_read_b64_tr_b16 v[212:213], v14 offset:17600
	ds_read_b64_tr_b16 v[214:215], v14 offset:20160
	ds_read_b64_tr_b16 v[216:217], v14 offset:22528
	ds_read_b64_tr_b16 v[218:219], v14 offset:25088
	ds_read_b64_tr_b16 v[220:221], v14 offset:22592
	ds_read_b64_tr_b16 v[222:223], v14 offset:25152
	ds_read_b64_tr_b16 v[224:225], v14 offset:22656
	ds_read_b64_tr_b16 v[226:227], v14 offset:25216
	ds_read_b64_tr_b16 v[228:229], v14 offset:22720
	ds_read_b64_tr_b16 v[230:231], v14 offset:25280
	ds_read_b64_tr_b16 v[232:233], v14 offset:27648
	ds_read_b64_tr_b16 v[234:235], v14 offset:30208
	ds_read_b64_tr_b16 v[236:237], v14 offset:27712
	ds_read_b64_tr_b16 v[238:239], v14 offset:30272
	ds_read_b64_tr_b16 v[240:241], v14 offset:27776
	ds_read_b64_tr_b16 v[242:243], v14 offset:30336
	ds_read_b64_tr_b16 v[244:245], v14 offset:27840
	ds_read_b64_tr_b16 v[246:247], v14 offset:30400
	ds_read_b64_tr_b16 v[248:249], v14 offset:32768
	ds_read_b64_tr_b16 v[250:251], v14 offset:35328
	ds_read_b64_tr_b16 v[156:157], v14 offset:32832
	ds_read_b64_tr_b16 v[158:159], v14 offset:35392
	ds_read_b64_tr_b16 v[160:161], v14 offset:32896
	ds_read_b64_tr_b16 v[162:163], v14 offset:35456
	ds_read_b64_tr_b16 v[164:165], v14 offset:32960
	ds_read_b64_tr_b16 v[166:167], v14 offset:35520
	s_and_b64 s[22:23], s[0:1], exec
	s_cselect_b32 s23, s26, s34
	s_cselect_b32 s22, s25, s27
	s_add_i32 s35, s24, s7
	s_mov_b32 m0, s35
	s_nop 0
	global_load_lds_dwordx4 v132, s[22:23]
	s_add_i32 s35, s24, s10
	s_addk_i32 s35, 0x400
	s_mov_b32 m0, s35
	s_nop 0
	global_load_lds_dwordx4 v131, s[22:23]
	s_and_b64 s[22:23], exec, s[8:9]
	s_cselect_b32 s23, s26, s34
	s_cselect_b32 s22, s25, s27
	s_add_i32 s35, s24, s11
	s_addk_i32 s35, 0x800
	s_mov_b32 m0, s35
	s_nop 0
	global_load_lds_dwordx4 v130, s[22:23]
	s_add_i32 s35, s24, s12
	s_addk_i32 s35, 0xc00
	s_mov_b32 m0, s35
	s_nop 0
	global_load_lds_dwordx4 v129, s[22:23]
	s_add_i32 s35, s24, s13
	s_addk_i32 s35, 0x1000
	s_mov_b32 m0, s35
	s_nop 0
	global_load_lds_dwordx4 v133, s[22:23]
	s_waitcnt vmcnt(10)
	s_waitcnt lgkmcnt(0)
	s_barrier
; #define LAS __attribute__((address_space(3)))
; DI s16x4 vtr(const LAS char* p) { return __builtin_bit_cast(s16x4, __builtin_amdgcn_ds_read_tr16_b64_v4i16((LAS v4i16_t*)p)); }
; DI bf16x8 cat4(s16x4 lo, s16x4 hi) { return __builtin_shufflevector(lo, hi, 0, 1, 2, 3, 4, 5, 6, 7); }
; #define SGB(mask, n) __builtin_amdgcn_sched_group_barrier((mask), (n), 0)
; DI void attn_qk(const LAS char* kb, const bf16x8 (&qf)[4], bf16x8 (&pf)[4], float& l) {
;     ...
;     f32x16 st0 = MFMA32(k0[0], qf[0], zero), st1 = MFMA32(k1[0], qf[0], zero);
; #pragma unroll
;     for (int s = 1; s < 4; ++s) { st0 = MFMA32(k0[s], qf[s], st0); st1 = MFMA32(k1[s], qf[s], st1); }
;     SGB(0x100, 8); SGB(0x008, 8);
;     float sum = 0.f;
; #pragma unroll
;     for (int i = 0; i < 16; ++i) { const float e = __builtin_amdgcn_exp2f(st0[i]); st0[i] = e; sum += e; }
;     pf[0] = pack8(st0, 0); pf[1] = pack8(st0, 1);
; #pragma unroll
;     for (int i = 0; i < 16; ++i) { const float e = __builtin_amdgcn_exp2f(st1[i]); st1[i] = e; sum += e; }
;     pf[2] = pack8(st1, 0); pf[3] = pack8(st1, 1);
;     l += sum;
; }
; DI void attn_pv(const LAS char* vb, const bf16x8 (&pf)[4], f32x16 (&O)[4]) {
;     s16x4 va[8], vc[8];
; #pragma unroll
;     for (int ks = 0; ks < 4; ++ks) { va[2 * ks] = vtr(vb + ks * 16 * VRS); va[2 * ks + 1] = vtr(vb + (ks * 16 + 8) * VRS); }
; #pragma unroll
;     for (int ks = 0; ks < 4; ++ks) { vc[2 * ks] = vtr(vb + ks * 16 * VRS + 64); vc[2 * ks + 1] = vtr(vb + (ks * 16 + 8) * VRS + 64); }
; #pragma unroll
;     for (int ks = 0; ks < 4; ++ks) O[0] = MFMA32(cat4(va[2 * ks], va[2 * ks + 1]), pf[ks], O[0]);
; #pragma unroll
;     for (int ks = 0; ks < 4; ++ks) { va[2 * ks] = vtr(vb + ks * 16 * VRS + 128); va[2 * ks + 1] = vtr(vb + (ks * 16 + 8) * VRS + 128); }
;     SGB(0x100, 16); SGB(0x008, 4); SGB(0x100, 8);
; #pragma unroll
;     for (int ks = 0; ks < 4; ++ks) O[1] = MFMA32(cat4(vc[2 * ks], vc[2 * ks + 1]), pf[ks], O[1]);
; #pragma unroll
;     for (int ks = 0; ks < 4; ++ks) { vc[2 * ks] = vtr(vb + ks * 16 * VRS + 192); vc[2 * ks + 1] = vtr(vb + (ks * 16 + 8) * VRS + 192); }
;     SGB(0x008, 4); SGB(0x100, 8);
; #pragma unroll
;     for (int ks = 0; ks < 4; ++ks) O[2] = MFMA32(cat4(va[2 * ks], va[2 * ks + 1]), pf[ks], O[2]);
;     SGB(0x008, 4);
; #pragma unroll
;     for (int ks = 0; ks < 4; ++ks) O[3] = MFMA32(cat4(vc[2 * ks], vc[2 * ks + 1]), pf[ks], O[3]);
;     SGB(0x008, 4);
	v_mfma_f32_32x32x16_bf16 v[96:111], v[2:5], v[112:115], 0
	v_mfma_f32_32x32x16_bf16 v[96:111], v[6:9], v[116:119], v[96:111]
	v_mfma_f32_32x32x16_bf16 v[96:111], v[10:13], v[120:123], v[96:111]
	v_mfma_f32_32x32x16_bf16 v[96:111], v[136:139], v[124:127], v[96:111]
	s_nop 7
	s_nop 2
	v_mfma_f32_32x32x16_bf16 v[80:95], v[140:143], v[112:115], 0
	v_exp_f32_e32 v96, v96
	v_exp_f32_e32 v97, v97
	s_nop 0
	v_add_f32_e32 v15, v96, v97
	v_mfma_f32_32x32x16_bf16 v[80:95], v[144:147], v[116:119], v[80:95]
	v_exp_f32_e32 v98, v98
	v_exp_f32_e32 v99, v99
	v_cvt_pk_bf16_f32 v96, v96, v97
	v_add_f32_e32 v15, v98, v15
	v_mfma_f32_32x32x16_bf16 v[80:95], v[148:151], v[120:123], v[80:95]
	v_exp_f32_e32 v100, v100
	v_exp_f32_e32 v101, v101
	v_cvt_pk_bf16_f32 v97, v98, v99
	v_add_f32_e32 v15, v99, v15
	v_mfma_f32_32x32x16_bf16 v[80:95], v[196:199], v[124:127], v[80:95]
	v_exp_f32_e32 v102, v102
	v_exp_f32_e32 v103, v103
	v_cvt_pk_bf16_f32 v98, v100, v101
	v_cvt_pk_bf16_f32 v99, v102, v103
	s_nop 1
	v_mfma_f32_32x32x16_bf16 v[64:79], v[200:203], v[96:99], v[64:79]
	v_exp_f32_e32 v104, v104
	v_exp_f32_e32 v105, v105
	v_add_f32_e32 v15, v104, v15
	v_add_f32_e32 v15, v105, v15
	v_mfma_f32_32x32x16_bf16 v[48:63], v[204:207], v[96:99], v[48:63]
	v_exp_f32_e32 v106, v106
	v_exp_f32_e32 v107, v107
	v_cvt_pk_bf16_f32 v104, v104, v105
	v_add_f32_e32 v15, v106, v15
	v_mfma_f32_32x32x16_bf16 v[32:47], v[208:211], v[96:99], v[32:47]
	v_exp_f32_e32 v108, v108
	v_exp_f32_e32 v109, v109
	v_cvt_pk_bf16_f32 v105, v106, v107
	v_add_f32_e32 v15, v107, v15
	v_mfma_f32_32x32x16_bf16 v[16:31], v[212:215], v[96:99], v[16:31]
	v_exp_f32_e32 v110, v110
	v_exp_f32_e32 v111, v111
	v_cvt_pk_bf16_f32 v106, v108, v109
	v_cvt_pk_bf16_f32 v107, v110, v111
	s_nop 1
	v_mfma_f32_32x32x16_bf16 v[64:79], v[216:219], v[104:107], v[64:79]
	v_exp_f32_e32 v80, v80
	v_exp_f32_e32 v81, v81
	v_add_f32_e32 v15, v80, v15
	v_add_f32_e32 v15, v81, v15
	v_mfma_f32_32x32x16_bf16 v[48:63], v[220:223], v[104:107], v[48:63]
	v_exp_f32_e32 v82, v82
	v_exp_f32_e32 v83, v83
	v_cvt_pk_bf16_f32 v80, v80, v81
	v_add_f32_e32 v15, v82, v15
	v_mfma_f32_32x32x16_bf16 v[32:47], v[224:227], v[104:107], v[32:47]
	v_exp_f32_e32 v84, v84
	v_exp_f32_e32 v85, v85
	v_cvt_pk_bf16_f32 v81, v82, v83
	v_add_f32_e32 v15, v83, v15
	v_mfma_f32_32x32x16_bf16 v[16:31], v[228:231], v[104:107], v[16:31]
	v_exp_f32_e32 v86, v86
	v_exp_f32_e32 v87, v87
	v_cvt_pk_bf16_f32 v82, v84, v85
	v_cvt_pk_bf16_f32 v83, v86, v87
	s_nop 1
	v_mfma_f32_32x32x16_bf16 v[64:79], v[232:235], v[80:83], v[64:79]
	v_exp_f32_e32 v88, v88
	v_exp_f32_e32 v89, v89
	v_add_f32_e32 v15, v88, v15
	v_add_f32_e32 v15, v89, v15
	v_mfma_f32_32x32x16_bf16 v[48:63], v[236:239], v[80:83], v[48:63]
	v_exp_f32_e32 v90, v90
	v_exp_f32_e32 v91, v91
	v_cvt_pk_bf16_f32 v88, v88, v89
	v_add_f32_e32 v15, v90, v15
	v_mfma_f32_32x32x16_bf16 v[32:47], v[240:243], v[80:83], v[32:47]
	v_exp_f32_e32 v92, v92
	v_exp_f32_e32 v93, v93
	v_cvt_pk_bf16_f32 v89, v90, v91
	v_add_f32_e32 v15, v91, v15
	v_mfma_f32_32x32x16_bf16 v[16:31], v[244:247], v[80:83], v[16:31]
	v_exp_f32_e32 v94, v94
	v_exp_f32_e32 v95, v95
	v_cvt_pk_bf16_f32 v90, v92, v93
	v_cvt_pk_bf16_f32 v91, v94, v95
	s_nop 1
	v_mfma_f32_32x32x16_bf16 v[64:79], v[248:251], v[88:91], v[64:79]
	v_add_f32_e32 v15, v100, v15
	v_add_f32_e32 v15, v101, v15
	v_add_f32_e32 v15, v102, v15
	v_add_f32_e32 v15, v103, v15
	v_mfma_f32_32x32x16_bf16 v[48:63], v[156:159], v[88:91], v[48:63]
	v_add_f32_e32 v15, v108, v15
	v_add_f32_e32 v15, v109, v15
	v_add_f32_e32 v15, v110, v15
	v_add_f32_e32 v15, v111, v15
	v_mfma_f32_32x32x16_bf16 v[32:47], v[160:163], v[88:91], v[32:47]
	v_add_f32_e32 v15, v84, v15
	v_add_f32_e32 v15, v85, v15
	v_add_f32_e32 v15, v86, v15
	v_add_f32_e32 v15, v87, v15
	v_mfma_f32_32x32x16_bf16 v[16:31], v[164:167], v[88:91], v[16:31]
	v_add_f32_e32 v15, v92, v15
	v_add_f32_e32 v15, v93, v15
	v_add_f32_e32 v15, v94, v15
	v_add_f32_e32 v15, v95, v15
	v_add_f32_e32 v175, v175, v15
	s_barrier
	s_branch .LBB0_744
.LattnB_skip:
	s_and_b64 s[22:23], s[0:1], exec
	s_cselect_b32 s23, s26, s34
	s_cselect_b32 s22, s25, s27
	s_add_i32 s35, s24, s7
	s_mov_b32 m0, s35
	s_nop 0
	global_load_lds_dwordx4 v132, s[22:23]
	s_add_i32 s35, s24, s10
	s_addk_i32 s35, 0x400
	s_mov_b32 m0, s35
	s_nop 0
	global_load_lds_dwordx4 v131, s[22:23]
	s_and_b64 s[22:23], exec, s[8:9]
	s_cselect_b32 s23, s26, s34
	s_cselect_b32 s22, s25, s27
	s_add_i32 s35, s24, s11
	s_addk_i32 s35, 0x800
	s_mov_b32 m0, s35
	s_nop 0
	global_load_lds_dwordx4 v130, s[22:23]
	s_add_i32 s35, s24, s12
	s_addk_i32 s35, 0xc00
	s_mov_b32 m0, s35
	s_nop 0
	global_load_lds_dwordx4 v129, s[22:23]
	s_add_i32 s35, s24, s13
	s_addk_i32 s35, 0x1000
	s_mov_b32 m0, s35
	s_nop 0
	global_load_lds_dwordx4 v133, s[22:23]
	s_waitcnt vmcnt(10)
	s_barrier
	s_barrier
	s_branch .LBB0_744
